# k10 + mirror of the static priority raise: s_setprio 1 for waves 0-3 over each differential block
# speedup vs baseline: 1.0047x; 1.0024x over previous
.LBB0_396:
	s_cmp_lt_u32 s3, 4
	s_cbranch_scc0 .Lprio_skip
	s_setprio 1
